# attention: halves staggered by half a round (two barriers per round, waves 4-7 one barrier behind)
# speedup vs baseline: 1.0030x; 1.0015x over previous
; #define LAS __attribute__((address_space(3)))
; __device__ __forceinline__ int ltid() { int t = threadIdx.x; asm volatile("" : "+v"(t)); return t; }
; __device__ __forceinline__ void attn_phase(LAS unsigned char* lds, bf16_t* qkv, float* lse, const float* biasT, int G) {
;     const int tid = ltid(), wave = __builtin_amdgcn_readfirstlane(tid >> 6), lane = tid & 63, half = wave >> 2, w4 = wave & 3, li = lane & 15, lg = lane >> 4, ht = tid & 255;
;     LAS unsigned char* vs = lds + half * VS_BYTES;
;     LAS float* bs = (LAS float*)(lds + 2 * VS_BYTES + half * 1024);
;     const float scale2 = 0.08838834764831845f * 1.4426950408889634f;
;     for (int i = ht; i < 16 * VS_PITCH / 16; i += 256) *(LAS u32x4*)(vs + 192 * VS_PITCH + i * 16) = (u32x4){0u, 0u, 0u, 0u};
;     if (ht < 176) bs[ht] = 0.f;
;     const int dl = 4 * lg - li, q4 = li >> 2, p4 = li & 3;
;     const LAS float* bsl = bs + 16 + dl;
;     const LAS unsigned char* vrd = vs + (16 * w4 + 4 * lg + q4) * VS_PITCH + (4 * p4) * 2;
;     u32x4 vreg[12];
;     const int nrounds = (4608 + G - 1) / G, cwg = blockIdx.x;
;     { const int pair0 = attn_pair(0, cwg, G); if (pair0 < 4608) { const AttnItem a = attn_item(pair0 * 2 + half); attn_load_v(a, qkv, ht, vreg); } }
;     __syncthreads();
.LBB0_410:
	v_readlane_b32 s0, v251, 12
	v_readlane_b32 s1, v251, 13
	s_andn2_b64 vcc, exec, s[0:1]
	s_waitcnt lgkmcnt(0)
	s_barrier
	s_cbranch_vccnz .LBB0_458
	v_bfe_u32 v3, v56, 4, 2
	v_and_b32_e32 v216, 15, v56
	v_lshlrev_b32_e32 v182, 2, v3
	s_lshr_b32 s0, s11, 2
	v_sub_u32_e32 v217, v182, v216
	s_and_b32 s0, s0, 48
	v_readlane_b32 s8, v251, 63
	v_lshl_add_u32 v218, v217, 2, s12
	v_readlane_b32 s9, v250, 0
	s_add_u32 s12, s8, 0x3f240000
	s_addc_u32 s13, s9, 0
	v_writelane_b32 v250, s12, 13
	s_add_u32 s8, s8, 0.5
	s_addc_u32 s9, s9, 0
	v_writelane_b32 v250, s13, 14
	v_writelane_b32 v250, s8, 15
	s_movk_i32 s1, 0x81
	v_bfe_u32 v0, v56, 2, 2
	v_writelane_b32 v250, s9, 16
	v_cmp_gt_u32_e64 s[8:9], s1, v183
	v_or3_b32 v0, v0, v182, s0
	v_or_b32_e32 v184, s0, v216
	v_writelane_b32 v250, s8, 1
	s_orn2_b32 s0, s0, 63
	v_lshlrev_b32_e32 v2, 3, v56
	v_writelane_b32 v250, s9, 2
	v_writelane_b32 v250, s0, 21
	v_cmp_lt_i32_e64 s[0:1], -1, v217
	v_mul_u32_u24_e32 v0, 0x120, v0
	v_and_b32_e32 v2, 24, v2
	v_writelane_b32 v250, s0, 17
	v_add3_u32 v219, s10, v0, v2
	v_lshlrev_b32_e32 v0, 4, v56
	v_writelane_b32 v250, s1, 18
	v_cmp_lt_i32_e64 s[0:1], -2, v217
	v_and_b32_e32 v0, 0xf0, v0
	v_add_u32_e32 v54, s10, v0
	v_writelane_b32 v250, s0, 22
	v_lshlrev_b32_e32 v0, 4, v3
	v_lshlrev_b32_e32 v2, 3, v3
	v_writelane_b32 v250, s1, 23
	v_cmp_lt_i32_e64 s[0:1], -4, v217
	v_lshl_add_u64 v[186:187], s[92:93], 0, v[0:1]
	v_mov_b32_e32 v53, v1
	v_writelane_b32 v250, s0, 24
	v_mul_u32_u24_e32 v0, 0x120, v215
	v_or_b32_e32 v220, 0xffffffc0, v215
	v_writelane_b32 v250, s1, 25
	v_cmp_lt_i32_e64 s[0:1], -3, v217
	v_lshl_add_u64 v[188:189], s[92:93], 0, v[52:53]
	v_or_b32_e32 v221, 0xffffffd0, v215
	v_writelane_b32 v251, s0, 63
	v_or_b32_e32 v222, 0xffffffe0, v215
	v_or_b32_e32 v223, -16, v215
	v_writelane_b32 v250, s1, 0
	v_cmp_gt_i32_e64 s[0:1], 0, v217
	v_or_b32_e32 v224, 16, v215
	v_or_b32_e32 v225, 32, v215
	v_writelane_b32 v250, s0, 11
	v_or_b32_e32 v226, 48, v215
	v_or_b32_e32 v227, 64, v215
	v_writelane_b32 v250, s1, 12
	v_cmp_gt_i32_e64 s[0:1], 1, v217
	v_or_b32_e32 v228, 0x50, v215
	v_or_b32_e32 v229, 0x60, v215
	v_or_b32_e32 v230, 0x70, v215
	s_mov_b32 s9, 0
	v_writelane_b32 v250, s0, 9
	v_cmp_gt_i32_e64 s[22:23], -1, v217
	v_cmp_gt_i32_e64 s[34:35], -2, v217
	v_cmp_eq_u32_e64 s[26:27], 0, v3
	v_add_u32_e32 v231, v54, v0
	v_lshlrev_b32_e32 v190, 1, v2
	v_lshlrev_b32_e32 v192, 1, v182
	v_readlane_b32 s97, v251, 31
	v_writelane_b32 v250, s1, 10
	s_cmp_lg_u32 s94, 0
	s_cbranch_scc0 .Lattn_stag_in
	s_barrier
.Lattn_stag_in:
	s_branch .LBB0_414
.LBB0_412:
	s_or_b64 exec, exec, s[0:1]
	v_readlane_b32 s0, v251, 30
	s_add_i32 s10, s97, s0
	v_readlane_b32 s0, v251, 11
	s_cmp_eq_u32 s0, s8
	s_cselect_b64 s[0:1], -1, 0
	s_barrier

; #define ATT_LOADK(buf, grp) do { _Pragma("unroll") for (int tt = 0; tt < 3; ++tt) { int ki = kbase + 16 * ((grp) * 3 + tt); ki = ki < 0 ? 0 : (ki > a.m - 1 ? a.m - 1 : ki); \
;             const bf16_t* kp = kcol + (size_t)ki * 128; \
;             _Pragma("unroll") for (int ks = 0; ks < 4; ++ks) Kf[buf][tt][ks] = *(const bf16x8*)(kp + 32 * ks); } } while (0)
; #define ATT_MMAK(buf, grp) do { _Pragma("unroll") for (int tt = 0; tt < 3; ++tt) { f32x4 acc_ = (f32x4){0.f, 0.f, 0.f, 0.f}; \
;             _Pragma("unroll") for (int ks = 0; ks < 4; ++ks) acc_ = __builtin_amdgcn_mfma_f32_16x16x32_bf16(Kf[buf][tt][ks], Qf[ks], acc_, 0, 0, 0); sa[(grp) * 3 + tt] = acc_; } } while (0)
; __device__ __forceinline__ void attn_phase(LAS unsigned char* lds, bf16_t* qkv, float* lse, const float* biasT, int G) {
;     ...
;         const size_t tokq = (size_t)(a.pos0 + a.r + ((16 * w4 + li) << a.dsh));
;         const int pbase = a.seq_base + a.r * a.m;
;         bf16_t* qp = qkv + ((size_t)a.head * M_TOK + pbase + a.i0 + 16 * w4 + li) * 128;
;         bf16x8 Qf[4];
; #pragma unroll
;         for (int ks = 0; ks < 4; ++ks) Qf[ks] = *(const bf16x8*)(qp + 32 * ks + 8 * lg);
;         const int kbase = a.i0 - 64 + 16 * w4 + li;
;         const bf16_t* kcol = qkv + ((size_t)(12 + a.head) * M_TOK + pbase) * 128 + 8 * lg;
;         f32x4 sa[10];
;         bf16x8 Kf[2][3][4];
;     ...
;         ATT_LOADK(0, 0); ATT_LOADK(1, 1);
;         __builtin_amdgcn_sched_barrier(0);
;         ATT_MMAK(0, 0);
;         __builtin_amdgcn_sched_barrier(0);
;         ATT_LOADK(0, 2);
;         if (pairn < 4608) { const AttnItem an = attn_item(pairn * 2 + half); attn_load_v(an, qkv, ht, vreg); }
.LBB0_425:
	s_or_b64 exec, exec, s[0:1]
	s_mul_i32 s0, s10, 0xfffffd00
	s_add_i32 s0, s0, s9
	s_lshl_b32 s1, s0, 6
	s_and_b32 s9, s1, 0xffffe000
	s_cmpk_lt_i32 s0, 0x200
	s_cselect_b32 s0, 13, 14
	s_cselect_b32 s9, s9, 0x8000
	s_ashr_i32 s11, s10, 1
	s_and_b32 s12, s11, -2
	s_sub_i32 s11, s0, s12
	s_sub_i32 s30, s1, s9
	s_ashr_i32 s96, s30, s11
	s_lshl_b32 s31, s96, s11
	s_sub_i32 s13, s30, s31
	s_add_i32 s16, s31, s9
	s_mul_hi_i32 s0, s10, 0xc000
	s_ashr_i32 s18, s16, 31
	s_ashr_i32 s1, s13, 31
	s_mul_i32 s17, s10, 0xc000
	v_mov_b32_e32 v3, s0
	s_add_u32 s0, s13, s16
	v_or_b32_e32 v2, s17, v184
	s_addc_u32 s1, s1, s18
	v_lshl_add_u64 v[2:3], s[0:1], 0, v[2:3]
	v_readlane_b32 s0, v250, 21
	s_add_i32 s15, s13, s0
	s_add_i32 s0, s10, 12
	s_add_i32 s17, s17, 0x90000
	v_lshlrev_b64 v[2:3], 8, v[2:3]
	s_mul_hi_i32 s1, s0, 0xc000
	s_add_u32 s0, s17, s16
	v_lshl_add_u64 v[194:195], s[92:93], 0, v[2:3]
	v_mov_b32_e32 v191, v1
	s_addc_u32 s1, s1, s18
	v_lshl_add_u64 v[2:3], v[194:195], 0, v[190:191]
	s_lshl_b64 s[0:1], s[0:1], 8
	global_load_dwordx4 v[96:99], v[2:3], off
	global_load_dwordx4 v[92:95], v[2:3], off offset:64
	global_load_dwordx4 v[88:91], v[2:3], off offset:128
	global_load_dwordx4 v[52:55], v[2:3], off offset:192
	v_add_u32_e32 v0, s15, v216
	v_lshl_add_u64 v[2:3], v[186:187], 0, s[0:1]
	s_bfm_b32 s0, s11, 0
	v_min_i32_e32 v56, s0, v0
	v_ashrrev_i32_e32 v57, 31, v56
	v_lshlrev_b64 v[56:57], 7, v[56:57]
	v_cmp_lt_i32_e32 vcc, -1, v0
	s_movk_i32 s1, 0xffef
	v_add_u32_e32 v58, 48, v0
	v_cndmask_b32_e32 v57, 0, v57, vcc
	v_cndmask_b32_e32 v56, 0, v56, vcc
	v_lshl_add_u64 v[56:57], v[56:57], 1, v[2:3]
	global_load_dwordx4 v[68:71], v[56:57], off
	global_load_dwordx4 v[72:75], v[56:57], off offset:64
	global_load_dwordx4 v[80:83], v[56:57], off offset:128
	global_load_dwordx4 v[84:87], v[56:57], off offset:192
	v_add_u32_e32 v56, 16, v0
	v_min_i32_e32 v56, s0, v56
	v_ashrrev_i32_e32 v57, 31, v56
	v_lshlrev_b64 v[56:57], 7, v[56:57]
	v_cmp_lt_i32_e32 vcc, s1, v0
	s_movk_i32 s1, 0xffdf
	v_add_u32_e32 v102, 64, v0
	v_cndmask_b32_e32 v57, 0, v57, vcc
	v_cndmask_b32_e32 v56, 0, v56, vcc
	v_lshl_add_u64 v[56:57], v[56:57], 1, v[2:3]
	global_load_dwordx4 v[116:119], v[56:57], off
	global_load_dwordx4 v[136:139], v[56:57], off offset:64
	global_load_dwordx4 v[140:143], v[56:57], off offset:128
	global_load_dwordx4 v[144:147], v[56:57], off offset:192
	v_add_u32_e32 v56, 32, v0
	v_min_i32_e32 v56, s0, v56
	v_ashrrev_i32_e32 v57, 31, v56
	v_lshlrev_b64 v[56:57], 7, v[56:57]
	v_cmp_lt_i32_e32 vcc, s1, v0
	v_min_i32_e32 v100, s0, v102
	v_add_u32_e32 v122, 0x50, v0
	v_cndmask_b32_e32 v57, 0, v57, vcc
	v_cndmask_b32_e32 v56, 0, v56, vcc
	v_lshl_add_u64 v[56:57], v[56:57], 1, v[2:3]
	global_load_dwordx4 v[148:151], v[56:57], off
	global_load_dwordx4 v[152:155], v[56:57], off offset:64
	global_load_dwordx4 v[156:159], v[56:57], off offset:128
	global_load_dwordx4 v[160:163], v[56:57], off offset:192
	v_min_i32_e32 v56, s0, v58
	v_ashrrev_i32_e32 v57, 31, v56
	v_lshlrev_b64 v[56:57], 7, v[56:57]
	v_cmp_lt_i32_e32 vcc, -1, v58
	v_ashrrev_i32_e32 v101, 31, v100
	v_min_i32_e32 v120, s0, v122
	v_cndmask_b32_e32 v57, 0, v57, vcc
	v_cndmask_b32_e32 v56, 0, v56, vcc
	v_lshlrev_b64 v[100:101], 7, v[100:101]
	v_cmp_lt_i32_e32 vcc, -1, v102
	v_ashrrev_i32_e32 v121, 31, v120
	v_lshlrev_b64 v[120:121], 7, v[120:121]
	v_cndmask_b32_e32 v101, 0, v101, vcc
	v_cndmask_b32_e32 v100, 0, v100, vcc
	v_cmp_lt_i32_e32 vcc, -1, v122
	v_lshl_add_u64 v[76:77], v[56:57], 1, v[2:3]
	v_lshl_add_u64 v[112:113], v[100:101], 1, v[2:3]
	v_cndmask_b32_e32 v121, 0, v121, vcc
	v_cndmask_b32_e32 v120, 0, v120, vcc
	v_lshl_add_u64 v[132:133], v[120:121], 1, v[2:3]
	global_load_dwordx4 v[56:59], v[76:77], off
	global_load_dwordx4 v[60:63], v[76:77], off offset:64
	global_load_dwordx4 v[64:67], v[76:77], off offset:128
	s_nop 0
	global_load_dwordx4 v[76:79], v[76:77], off offset:192
	s_nop 0
	global_load_dwordx4 v[100:103], v[112:113], off
	global_load_dwordx4 v[104:107], v[112:113], off offset:64
	global_load_dwordx4 v[108:111], v[112:113], off offset:128
	s_nop 0
	global_load_dwordx4 v[112:115], v[112:113], off offset:192
	s_nop 0
	global_load_dwordx4 v[120:123], v[132:133], off
	global_load_dwordx4 v[124:127], v[132:133], off offset:64
	global_load_dwordx4 v[128:131], v[132:133], off offset:128
	s_nop 0
	global_load_dwordx4 v[132:135], v[132:133], off offset:192
	s_waitcnt vmcnt(23)
	v_mfma_f32_16x16x32_bf16 v[68:71], v[68:71], v[96:99], 0
	s_waitcnt vmcnt(22)
	v_mfma_f32_16x16x32_bf16 v[68:71], v[72:75], v[92:95], v[68:71]
	s_waitcnt vmcnt(21)
	v_mfma_f32_16x16x32_bf16 v[68:71], v[80:83], v[88:91], v[68:71]
	s_waitcnt vmcnt(20)
	v_mfma_f32_16x16x32_bf16 v[84:87], v[84:87], v[52:55], v[68:71]
	s_waitcnt vmcnt(19)
	v_mfma_f32_16x16x32_bf16 v[68:71], v[116:119], v[96:99], 0
	s_waitcnt vmcnt(18)
	v_mfma_f32_16x16x32_bf16 v[68:71], v[136:139], v[92:95], v[68:71]
	s_waitcnt vmcnt(17)
	v_mfma_f32_16x16x32_bf16 v[68:71], v[140:143], v[88:91], v[68:71]
	s_waitcnt vmcnt(16)
	v_mfma_f32_16x16x32_bf16 v[72:75], v[144:147], v[52:55], v[68:71]
	s_waitcnt vmcnt(15)
	v_mfma_f32_16x16x32_bf16 v[68:71], v[148:151], v[96:99], 0
	s_waitcnt vmcnt(14)
	v_mfma_f32_16x16x32_bf16 v[68:71], v[152:155], v[92:95], v[68:71]
	s_waitcnt vmcnt(13)
	v_mfma_f32_16x16x32_bf16 v[68:71], v[156:159], v[88:91], v[68:71]
	s_waitcnt vmcnt(12)
	v_mfma_f32_16x16x32_bf16 v[68:71], v[160:163], v[52:55], v[68:71]
	v_add_u32_e32 v82, 0x60, v0
	v_min_i32_e32 v80, s0, v82
	v_ashrrev_i32_e32 v81, 31, v80
	v_lshlrev_b64 v[80:81], 7, v[80:81]
	v_cmp_lt_i32_e32 vcc, -1, v82
	v_add_u32_e32 v82, 0x70, v0
	v_add_u32_e32 v0, 0x80, v0
	v_cndmask_b32_e32 v81, 0, v81, vcc
	v_cndmask_b32_e32 v80, 0, v80, vcc
	v_lshl_add_u64 v[80:81], v[80:81], 1, v[2:3]
	global_load_dwordx4 v[136:139], v[80:81], off
	global_load_dwordx4 v[140:143], v[80:81], off offset:64
	global_load_dwordx4 v[144:147], v[80:81], off offset:128
	global_load_dwordx4 v[148:151], v[80:81], off offset:192
	v_min_i32_e32 v80, s0, v82
	v_ashrrev_i32_e32 v81, 31, v80
	v_lshlrev_b64 v[80:81], 7, v[80:81]
	v_cmp_lt_i32_e32 vcc, -1, v82
	s_cmpk_gt_i32 s14, 0x11ff
	s_nop 0
	v_cndmask_b32_e32 v81, 0, v81, vcc
	v_cndmask_b32_e32 v80, 0, v80, vcc
	v_lshl_add_u64 v[80:81], v[80:81], 1, v[2:3]
	global_load_dwordx4 v[152:155], v[80:81], off
	global_load_dwordx4 v[156:159], v[80:81], off offset:64
	global_load_dwordx4 v[160:163], v[80:81], off offset:128
	global_load_dwordx4 v[164:167], v[80:81], off offset:192
	v_min_i32_e32 v80, s0, v0
	v_ashrrev_i32_e32 v81, 31, v80
	v_lshlrev_b64 v[80:81], 7, v[80:81]
	v_cmp_lt_i32_e32 vcc, -1, v0
	s_nop 1
	v_cndmask_b32_e32 v81, 0, v81, vcc
	v_cndmask_b32_e32 v80, 0, v80, vcc
	v_lshl_add_u64 v[2:3], v[80:81], 1, v[2:3]
	global_load_dwordx4 v[176:179], v[2:3], off
	global_load_dwordx4 v[172:175], v[2:3], off offset:64
	global_load_dwordx4 v[168:171], v[2:3], off offset:128
	global_load_dwordx4 v[116:119], v[2:3], off offset:192
	s_cbranch_scc1 .LBB0_451
; __device__ __forceinline__ AttnItem attn_item(int it) {
;     AttnItem a; a.head = it / 768; const int pb = it - a.head * 768, gi = a.head >> 2; a.dsh = gi * 2;
;     const int p0 = pb * 64; int lsh; if (p0 < 32768) { a.seq_base = p0 & ~8191; lsh = 13; } else { a.seq_base = 32768; lsh = 14; }
;     const int lm = lsh - a.dsh; a.m = 1 << lm; const int local = p0 - a.seq_base; a.r = local >> lm; a.i0 = local - (a.r << lm);
;     a.pos0 = a.seq_base + (a.i0 << a.dsh); return a;
; }
; __device__ __forceinline__ int attn_pair(int j, int c, int G) {
;     if ((G & 7) == 0 && (4608 % G) == 0) { const int per_xcd = 4608 / 8, wpx = G >> 3; return (c & 7) * per_xcd + j * wpx + (c >> 3); }
;     return j * G + c;
; }
; __device__ __forceinline__ void attn_load_v(const AttnItem& a, const bf16_t* qkv, int ht, u32x4 (&vreg)[12]) {
; #pragma unroll
;     for (int pass = 0; pass < 12; ++pass) {
;         const int row = pass * 16 + (ht >> 4), ch = ht & 15, ki = a.i0 - 64 + row;
;         u32x4 val = (u32x4){0u, 0u, 0u, 0u};
;         if (ki >= 0 && ki < a.m) val = *(const u32x4*)(qkv + ((size_t)(24 + a.head) * M_TOK + a.seq_base + a.r * a.m + ki) * 128 + ch * 8);
;         vreg[pass] = val;
;     }
; }
; __device__ __forceinline__ void attn_phase(LAS unsigned char* lds, bf16_t* qkv, float* lse, const float* biasT, int G) {
;     ...
;         if (pairn < 4608) { const AttnItem an = attn_item(pairn * 2 + half); attn_load_v(an, qkv, ht, vreg); }
	s_lshl_b32 s0, s14, 1
	s_add_i32 s0, s0, s94
	s_mul_hi_i32 s1, s0, 0x2aaaaaab
	s_lshr_b32 s14, s1, 31
	s_ashr_i32 s1, s1, 7
	s_add_i32 s14, s1, s14
	s_mul_i32 s1, s14, 0xfffffd00
	s_add_i32 s1, s1, s0
	s_lshl_b32 s0, s1, 6
	s_and_b32 s16, s0, 0xffffe000
	s_cmpk_lt_i32 s1, 0x200
	s_cselect_b32 s1, 13, 14
	s_cselect_b32 s16, s16, 0x8000
	s_ashr_i32 s17, s14, 1
	s_and_b32 s17, s17, -2
	s_sub_i32 s1, s1, s17
	s_lshl_b32 s18, 1, s1
	s_sub_i32 s0, s0, s16
	s_lshl_b32 s1, -1, s1
	s_and_b32 s17, s1, s0
	s_sub_i32 s19, s0, s17
	v_add_u32_e32 v0, s19, v220
	v_mov_b32_e32 v6, v1
	v_mov_b32_e32 v7, v1
	v_cmp_lt_i32_e32 vcc, -1, v0
	v_cmp_gt_i32_e64 s[0:1], s18, v0
	v_mov_b32_e32 v4, v1
	v_mov_b32_e32 v5, v1
	v_mov_b64_e32 v[10:11], v[6:7]
	s_and_b64 s[28:29], vcc, s[0:1]
	v_mov_b64_e32 v[8:9], v[4:5]
	s_and_saveexec_b64 s[0:1], s[28:29]
	s_cbranch_execz .LBB0_428
	s_add_i32 s28, s14, 24
	s_mul_hi_i32 s29, s28, 0xc000
	s_mul_i32 s28, s28, 0xc000
	s_ashr_i32 vcc_lo, s16, 31
	s_ashr_i32 vcc_hi, s17, 31
	s_add_u32 s28, s28, s16
	s_addc_u32 s29, s29, vcc_lo
	s_add_u32 s28, s28, s17
	s_addc_u32 s29, s29, vcc_hi
	v_lshl_add_u64 v[2:3], s[28:29], 0, v[0:1]
	v_lshlrev_b64 v[2:3], 8, v[2:3]
	v_lshl_add_u64 v[2:3], v[188:189], 0, v[2:3]
	global_load_dwordx4 v[8:11], v[2:3], off

; #define LAS __attribute__((address_space(3)))
; #define ATT_MMAK(buf, grp) do { _Pragma("unroll") for (int tt = 0; tt < 3; ++tt) { f32x4 acc_ = (f32x4){0.f, 0.f, 0.f, 0.f}; \
;             _Pragma("unroll") for (int ks = 0; ks < 4; ++ks) acc_ = __builtin_amdgcn_mfma_f32_16x16x32_bf16(Kf[buf][tt][ks], Qf[ks], acc_, 0, 0, 0); sa[(grp) * 3 + tt] = acc_; } } while (0)
; template <bool EDGE>
; __device__ __forceinline__ float attn_scores(f32x4 (&sa)[10], const LAS float* bsl, int dl, int kabs0, int m, float scale2) {
;     float mx = -3.0e38f;
; #pragma unroll
;     for (int t9 = 0; t9 < 9; ++t9)
; #pragma unroll
;         for (int j = 0; j < 4; ++j) {
;             bool valid = true;
;             if (t9 == 0) valid = (j + dl >= 0);
;             if (t9 == 8) valid = (j + dl <= 0);
;             if (EDGE) { const int kabs = kabs0 + 16 * t9 + j; valid = valid && (kabs >= 0) && (kabs < m); }
;             float sv = sa[t9][j] * scale2 + bsl[16 * t9 + j];
;             sv = valid ? sv : -1.0e30f;
;             sa[t9][j] = sv; mx = fmaxf(mx, sv);
;         }
;     return mx;
; }
; __device__ __forceinline__ void attn_phase(LAS unsigned char* lds, bf16_t* qkv, float* lse, const float* biasT, int G) {
;     ...
;         ATT_MMAK(1, 1);
;         ATT_MMAK(0, 2);
;     ...
;         sa[9] = (f32x4){0.f, 0.f, 0.f, 0.f};
;         const int kabs0 = a.i0 - 64 + 16 * w4 + 4 * lg;
;         const bool edge = (a.i0 == 0) || (a.i0 + 64 == a.m);
;         float mx = edge ? attn_scores<true>(sa, bsl, dl, kabs0, a.m, scale2) : attn_scores<false>(sa, bsl, dl, kabs0, a.m, scale2);
.LBB0_451:
	s_lshl_b32 s14, 1, s11
	s_ashr_i32 s11, s10, 31
	s_waitcnt vmcnt(23)
	v_mfma_f32_16x16x32_bf16 v[56:59], v[56:59], v[96:99], 0
	s_cmp_eq_u32 s30, s31
	s_cselect_b64 s[0:1], -1, 0
	s_add_i32 s16, s13, 64
	s_waitcnt vmcnt(22)
	v_mfma_f32_16x16x32_bf16 v[56:59], v[60:63], v[92:95], v[56:59]
	s_cmp_eq_u32 s16, s14
	s_cselect_b64 s[16:17], -1, 0
	s_or_b64 s[16:17], s[0:1], s[16:17]
	s_waitcnt vmcnt(21)
	v_mfma_f32_16x16x32_bf16 v[56:59], v[64:67], v[88:91], v[56:59]
	s_mov_b64 s[0:1], -1
	s_andn2_b64 vcc, exec, s[16:17]
	s_waitcnt vmcnt(20)
	v_mfma_f32_16x16x32_bf16 v[80:83], v[76:79], v[52:55], v[56:59]
	s_waitcnt vmcnt(19)
	v_mfma_f32_16x16x32_bf16 v[56:59], v[100:103], v[96:99], 0
	s_waitcnt vmcnt(18)
	v_mfma_f32_16x16x32_bf16 v[56:59], v[104:107], v[92:95], v[56:59]
	s_waitcnt vmcnt(17)
	v_mfma_f32_16x16x32_bf16 v[56:59], v[108:111], v[88:91], v[56:59]
	s_waitcnt vmcnt(16)
	v_mfma_f32_16x16x32_bf16 v[76:79], v[112:115], v[52:55], v[56:59]
	s_waitcnt vmcnt(15)
	v_mfma_f32_16x16x32_bf16 v[56:59], v[120:123], v[96:99], 0
	s_waitcnt vmcnt(14)
	v_mfma_f32_16x16x32_bf16 v[56:59], v[124:127], v[92:95], v[56:59]
	s_waitcnt vmcnt(13)
	v_mfma_f32_16x16x32_bf16 v[56:59], v[128:131], v[88:91], v[56:59]
	s_waitcnt vmcnt(12)
	v_mfma_f32_16x16x32_bf16 v[64:67], v[132:135], v[52:55], v[56:59]
	s_waitcnt vmcnt(11)
	v_mfma_f32_16x16x32_bf16 v[56:59], v[136:139], v[96:99], 0
	s_waitcnt vmcnt(10)
	v_mfma_f32_16x16x32_bf16 v[56:59], v[140:143], v[92:95], v[56:59]
	s_waitcnt vmcnt(9)
	v_mfma_f32_16x16x32_bf16 v[56:59], v[144:147], v[88:91], v[56:59]
	s_waitcnt vmcnt(8)
	v_mfma_f32_16x16x32_bf16 v[60:63], v[148:151], v[52:55], v[56:59]
	s_waitcnt vmcnt(7)
	v_mfma_f32_16x16x32_bf16 v[56:59], v[152:155], v[96:99], 0
	s_waitcnt vmcnt(3)
	v_mfma_f32_16x16x32_bf16 v[96:99], v[176:179], v[96:99], 0
	v_mfma_f32_16x16x32_bf16 v[56:59], v[156:159], v[92:95], v[56:59]
	s_waitcnt vmcnt(2)
	v_mfma_f32_16x16x32_bf16 v[92:95], v[172:175], v[92:95], v[96:99]
	v_mfma_f32_16x16x32_bf16 v[56:59], v[160:163], v[88:91], v[56:59]
	s_waitcnt vmcnt(1)
	v_mfma_f32_16x16x32_bf16 v[126:129], v[168:171], v[88:91], v[92:95]
	v_mfma_f32_16x16x32_bf16 v[56:59], v[164:167], v[52:55], v[56:59]
	s_waitcnt vmcnt(0)
	v_mfma_f32_16x16x32_bf16 v[52:55], v[116:119], v[52:55], v[126:129]
	s_waitcnt lgkmcnt(0)
	s_barrier
	s_cbranch_vccz .LBB0_453
	ds_read2_b32 v[2:3], v218 offset0:16 offset1:17
	s_mov_b32 s0, 0x3e0293ee
	v_readlane_b32 s16, v250, 22
	v_readlane_b32 s17, v250, 23
	s_waitcnt lgkmcnt(0)
	v_pk_fma_f32 v[2:3], v[84:85], s[0:1], v[2:3] op_sel_hi:[1,0,1]
	s_nop 0
	v_cndmask_b32_e64 v0, v212, v3, s[16:17]
	v_readlane_b32 s16, v250, 17
	v_readlane_b32 s17, v250, 18
	s_nop 1
	v_cndmask_b32_e64 v114, v212, v2, s[16:17]
	ds_read2_b32 v[2:3], v218 offset0:18 offset1:19
	v_readlane_b32 s16, v250, 24
	v_readlane_b32 s17, v250, 25
	v_max_f32_e32 v88, 0xff61b1e6, v114
	s_waitcnt lgkmcnt(0)
	v_pk_fma_f32 v[2:3], v[86:87], s[0:1], v[2:3] op_sel_hi:[1,0,1]
	s_nop 0
	v_cndmask_b32_e64 v120, v212, v3, s[16:17]
	v_readlane_b32 s16, v251, 63
	v_readlane_b32 s17, v250, 0
	s_nop 1
	v_cndmask_b32_e64 v115, v212, v2, s[16:17]
	ds_read2_b32 v[2:3], v218 offset0:32 offset1:33
	v_max3_f32 v88, v88, v0, v115
	s_waitcnt lgkmcnt(0)
	v_pk_fma_f32 v[2:3], v[72:73], s[0:1], v[2:3] op_sel_hi:[1,0,1]
	s_nop 0
	v_max3_f32 v90, v88, v120, v2
	ds_read2_b32 v[88:89], v218 offset0:34 offset1:35
	s_waitcnt lgkmcnt(0)
	v_pk_fma_f32 v[88:89], v[74:75], s[0:1], v[88:89] op_sel_hi:[1,0,1]
	s_nop 0
	v_max3_f32 v92, v90, v3, v88
	ds_read2_b32 v[90:91], v218 offset0:48 offset1:49
	s_waitcnt lgkmcnt(0)
	v_pk_fma_f32 v[90:91], v[68:69], s[0:1], v[90:91] op_sel_hi:[1,0,1]
	s_nop 0
	v_max3_f32 v94, v92, v89, v90
	ds_read2_b32 v[92:93], v218 offset0:50 offset1:51
	s_waitcnt lgkmcnt(0)
	v_pk_fma_f32 v[92:93], v[70:71], s[0:1], v[92:93] op_sel_hi:[1,0,1]
	s_nop 0
	v_max3_f32 v96, v94, v91, v92
	ds_read2_b32 v[94:95], v218 offset0:64 offset1:65
	s_waitcnt lgkmcnt(0)
	v_pk_fma_f32 v[94:95], v[80:81], s[0:1], v[94:95] op_sel_hi:[1,0,1]
	s_nop 0
	v_max3_f32 v98, v96, v93, v94
	ds_read2_b32 v[96:97], v218 offset0:66 offset1:67
	s_waitcnt lgkmcnt(0)
	v_pk_fma_f32 v[96:97], v[82:83], s[0:1], v[96:97] op_sel_hi:[1,0,1]
	s_nop 0
	v_max3_f32 v100, v98, v95, v96
	ds_read2_b32 v[98:99], v218 offset0:80 offset1:81
	s_waitcnt lgkmcnt(0)
	v_pk_fma_f32 v[98:99], v[76:77], s[0:1], v[98:99] op_sel_hi:[1,0,1]
	s_nop 0
	v_max3_f32 v102, v100, v97, v98
	ds_read2_b32 v[100:101], v218 offset0:82 offset1:83
	s_waitcnt lgkmcnt(0)
	v_pk_fma_f32 v[100:101], v[78:79], s[0:1], v[100:101] op_sel_hi:[1,0,1]
	s_nop 0
	v_max3_f32 v104, v102, v99, v100
	ds_read2_b32 v[102:103], v218 offset0:96 offset1:97
	s_waitcnt lgkmcnt(0)
	v_pk_fma_f32 v[102:103], v[64:65], s[0:1], v[102:103] op_sel_hi:[1,0,1]
	s_nop 0
	v_max3_f32 v106, v104, v101, v102
	ds_read2_b32 v[104:105], v218 offset0:98 offset1:99
	s_waitcnt lgkmcnt(0)
	v_pk_fma_f32 v[104:105], v[66:67], s[0:1], v[104:105] op_sel_hi:[1,0,1]
	s_nop 0
	v_max3_f32 v108, v106, v103, v104
	ds_read2_b32 v[106:107], v218 offset0:112 offset1:113
	s_waitcnt lgkmcnt(0)
	v_pk_fma_f32 v[106:107], v[60:61], s[0:1], v[106:107] op_sel_hi:[1,0,1]
	s_nop 0
	v_max3_f32 v110, v108, v105, v106
	ds_read2_b32 v[108:109], v218 offset0:114 offset1:115
	s_waitcnt lgkmcnt(0)
	v_pk_fma_f32 v[108:109], v[62:63], s[0:1], v[108:109] op_sel_hi:[1,0,1]
	s_nop 0
	v_max3_f32 v112, v110, v107, v108
	ds_read2_b32 v[110:111], v218 offset0:128 offset1:129
	s_waitcnt lgkmcnt(0)
	v_pk_fma_f32 v[110:111], v[56:57], s[0:1], v[110:111] op_sel_hi:[1,0,1]
	s_nop 0
	v_max3_f32 v116, v112, v109, v110
	ds_read2_b32 v[112:113], v218 offset0:130 offset1:131
	s_waitcnt lgkmcnt(0)
	v_pk_fma_f32 v[112:113], v[58:59], s[0:1], v[112:113] op_sel_hi:[1,0,1]
	s_nop 0
	v_max3_f32 v118, v116, v111, v112
	ds_read2_b32 v[116:117], v218 offset0:144 offset1:145
	s_waitcnt lgkmcnt(0)
	v_pk_fma_f32 v[116:117], v[52:53], s[0:1], v[116:117] op_sel_hi:[1,0,1]
	v_readlane_b32 s0, v250, 11
	v_readlane_b32 s1, v250, 12
	s_nop 1
	v_cndmask_b32_e64 v121, v212, v117, s[0:1]
	ds_read_b32 v117, v218 offset:584
	v_readlane_b32 s0, v250, 9
	v_readlane_b32 s1, v250, 10
	s_waitcnt lgkmcnt(0)
	v_fmac_f32_e32 v117, 0x3e0293ee, v54
	v_cndmask_b32_e64 v122, v212, v116, s[0:1]
	v_max3_f32 v116, v118, v113, v122
	v_cndmask_b32_e64 v123, v212, v117, s[22:23]
	v_max3_f32 v124, v116, v121, v123
	s_mov_b64 s[0:1], 0

; __device__ __forceinline__ void attn_phase(LAS unsigned char* lds, bf16_t* qkv, float* lse, const float* biasT, int G) {
;     ...
;         __syncthreads();
;     }
; }
.Lattn_exit:
	s_cmp_lg_u32 s94, 0
	s_cbranch_scc1 .LBB0_458
	s_barrier

; template <bool COOP>
; __global__ void __launch_bounds__(512, 2) fwd_kernel(Params p) {
;     ...
;     }
; }
.LBB0_641:
	s_nop 0
	s_nop 0
	s_nop 0
	s_nop 0
	s_nop 0
	s_nop 0
	s_nop 0
	s_nop 0
	s_nop 0
	s_nop 0
	s_nop 0
	s_nop 0
	s_nop 0
	s_nop 0
	s_nop 0
	s_nop 0
	s_nop 0
	s_nop 0
	s_nop 0
	s_nop 0
	s_nop 0
	s_nop 0
	s_nop 0
	s_nop 0
	s_nop 0
	s_nop 0
	s_nop 0
	s_nop 0
	s_nop 0
	s_nop 0
	s_nop 0
	s_nop 0
	s_nop 0
	s_nop 0
	s_nop 0
	s_nop 0
	s_nop 0
	s_nop 0
	s_nop 0
	s_nop 0
	s_nop 0
	s_nop 0
	s_nop 0
	s_nop 0
	s_nop 0
	s_nop 0
	s_nop 0
	s_nop 0
	s_nop 0
	s_nop 0
	s_nop 0
	s_nop 0
	s_nop 0
	s_nop 0
	s_nop 0
	s_nop 0
	s_nop 0
	s_nop 0
	s_nop 0
	s_nop 0
	s_nop 0
	s_nop 0
	s_nop 0
	s_nop 0
	s_nop 0
	s_nop 0
	s_nop 0
	s_nop 0
	s_nop 0
	s_nop 0
	s_nop 0
	s_nop 0
	s_nop 0
	s_nop 0
	s_nop 0
	s_nop 0
	s_nop 0
	s_nop 0
	s_nop 0
	s_nop 0
	s_nop 0
	s_nop 0
	s_nop 0
	s_nop 0
	s_nop 0
	s_nop 0
	s_nop 0
	s_nop 0
	s_nop 0
	s_nop 0
	s_nop 0
	s_nop 0
	s_nop 0
	s_nop 0
	s_nop 0
	s_nop 0
	s_endpgm
